# v54 with the whole instruction stream shifted by 4 bytes (one s_nop 0 at kernel entry): code-placement phase test
# speedup vs baseline: 1.0039x; 1.0039x over previous
; #define LAS __attribute__((address_space(3)))
; __device__ __forceinline__ unsigned xb_add(unsigned* p, unsigned v) { return __hip_atomic_fetch_add(p, v, __ATOMIC_RELAXED, __HIP_MEMORY_SCOPE_AGENT); }
; __device__ __forceinline__ unsigned xb_xcc_id() { return (unsigned)__builtin_amdgcn_s_getreg((3 << 11) | 20) & 0xFu; }
; __device__ __forceinline__ XcdBarrier xcd_barrier_post(unsigned* bar, volatile LAS unsigned* st) {
;     XcdBarrier b; b.bar = bar; b.x = xb_xcc_id(); b.st = st;
;     if (threadIdx.x == 0) (void)xb_add(&bar[XB_XCNT(b.x)], 1u);
;     return b;
; }
; __global__ void __launch_bounds__(512, 2) fwd_megakernel(Args a) {
;     extern __shared__ __attribute__((aligned(16))) unsigned char lds_raw[];
;     LAS unsigned char* lds = (LAS unsigned char*)lds_raw;
;     cg::grid_group grid = cg::this_grid();
;     unsigned char* ws = a.ws;
;     volatile LAS unsigned* bst = (volatile LAS unsigned*)(lds + LDS_TOP);
;     if (threadIdx.x < 2) bst[threadIdx.x] = 0u;
;     __syncthreads();
;     const XcdBarrier xbar = xcd_barrier_post((unsigned*)(ws + WS_BAR), bst);
_Z14fwd_megakernel4Args:
	s_nop 0
	s_load_dwordx16 s[16:31], s[0:1], 0x80
	s_load_dword s33, s[0:1], 0xd8
	s_load_dwordx4 s[68:71], s[0:1], 0xc0
	s_load_dwordx2 s[14:15], s[0:1], 0xd0
	s_add_u32 s4, s0, 0xd0
	v_and_b32_e32 v192, 0x3ff, v0
	s_mov_b32 s12, s2
	s_addc_u32 s5, s1, 0
	v_cmp_gt_u32_e32 vcc, 2, v192
	s_and_saveexec_b64 s[2:3], vcc
	v_lshl_add_u32 v1, v192, 2, 0
	v_add_u32_e32 v1, 0x25000, v1
	v_mov_b32_e32 v2, 0
	ds_write_b32 v1, v2
	s_or_b64 exec, exec, s[2:3]
	s_waitcnt lgkmcnt(0)
	s_barrier
	s_add_u32 s34, s30, 0x20000
	s_getreg_b32 s2, hwreg(HW_REG_XCC_ID, 0, 4)
	s_addc_u32 s35, s31, 0
	s_and_b32 s13, s2, 15
	v_cmp_eq_u32_e64 s[10:11], 0, v192
	s_and_saveexec_b64 s[2:3], s[10:11]
	s_cbranch_execz .LBB0_5
	s_mov_b64 s[6:7], exec
	v_mbcnt_lo_u32_b32 v1, s6, 0
	v_mbcnt_hi_u32_b32 v1, s7, v1
	v_cmp_eq_u32_e32 vcc, 0, v1
	s_and_b64 s[8:9], exec, vcc
	s_mov_b64 exec, s[8:9]
	s_cbranch_execz .LBB0_5
	s_lshl_b32 s8, s13, 8
	s_bcnt1_i32_b64 s6, s[6:7]
	v_mov_b32_e32 v1, s8
	v_mov_b32_e32 v2, s6
	global_atomic_add v1, v2, s[34:35] offset:1024
